# v68 + loop back-edge rotation on the four GEMM main loops (closing barrier below the counter/pointer/exit-test block)
# speedup vs baseline: 1.0025x; 1.0025x over previous
.LBB0_143:
	ds_read_b128 v[96:99], v183
	ds_read_b128 v[100:103], v183 offset:1024
	ds_read_b128 v[112:115], v183 offset:2048
	ds_read_b128 v[120:123], v183 offset:3072
	ds_read_b128 v[144:147], v184
	ds_read_b128 v[170:173], v184 offset:1024
	ds_read_b128 v[186:189], v184 offset:2048
	ds_read_b128 v[190:193], v184 offset:3072
	s_add_u32 s44, s0, 0xfffc0080
	s_addc_u32 s45, s1, -1
	s_cmp_eq_u32 s89, 12
	s_cselect_b32 s87, s77, s45
	s_cselect_b32 s86, vcc_lo, s44
	s_cselect_b32 s85, s75, s15
	s_cselect_b32 s84, vcc_hi, s14
	v_lshl_add_u64 v[194:195], s[0:1], 0, v[162:163]
	s_add_i32 m0, s92, 0xc000
	ds_read_b128 v[198:201], v185
	ds_read_b128 v[206:209], v185 offset:1024
	ds_read_b128 v[210:213], v185 offset:2048
	ds_read_b128 v[214:217], v185 offset:3072
	ds_read_b128 v[218:221], v185 offset:4096
	ds_read_b128 v[222:225], v185 offset:5120
	ds_read_b128 v[226:229], v185 offset:6144
	ds_read_b128 v[230:233], v185 offset:7168
	global_load_lds_dwordx4 v[194:195], off
	v_lshl_add_u64 v[194:195], s[0:1], 0, v[164:165]
	s_add_i32 m0, s92, 0xe000
	s_nop 0
	global_load_lds_dwordx4 v[194:195], off
	s_waitcnt vmcnt(8)
	s_waitcnt lgkmcnt(0)
	s_barrier
	s_setprio 1
	s_waitcnt lgkmcnt(0)
	v_mfma_f32_16x16x32_bf16 v[140:143], v[96:99], v[198:201], v[140:143]
	v_mfma_f32_16x16x32_bf16 v[136:139], v[112:115], v[198:201], v[136:139]
	v_mfma_f32_16x16x32_bf16 v[124:127], v[96:99], v[210:213], v[124:127]
	v_mfma_f32_16x16x32_bf16 v[116:119], v[112:115], v[210:213], v[116:119]
	v_mfma_f32_16x16x32_bf16 v[92:95], v[96:99], v[218:221], v[92:95]
	v_mfma_f32_16x16x32_bf16 v[88:91], v[112:115], v[218:221], v[88:91]
	v_mfma_f32_16x16x32_bf16 v[76:79], v[96:99], v[226:229], v[76:79]
	v_mfma_f32_16x16x32_bf16 v[72:75], v[112:115], v[226:229], v[72:75]
	v_mfma_f32_16x16x32_bf16 v[140:143], v[100:103], v[206:209], v[140:143]
	v_mfma_f32_16x16x32_bf16 v[136:139], v[120:123], v[206:209], v[136:139]
	v_mfma_f32_16x16x32_bf16 v[124:127], v[100:103], v[214:217], v[124:127]
	v_mfma_f32_16x16x32_bf16 v[116:119], v[120:123], v[214:217], v[116:119]
	v_mfma_f32_16x16x32_bf16 v[92:95], v[100:103], v[222:225], v[92:95]
	v_mfma_f32_16x16x32_bf16 v[88:91], v[120:123], v[222:225], v[88:91]
	v_mfma_f32_16x16x32_bf16 v[76:79], v[100:103], v[230:233], v[76:79]
	v_mfma_f32_16x16x32_bf16 v[72:75], v[120:123], v[230:233], v[72:75]
	s_setprio 0
	s_setprio 1
	v_mfma_f32_16x16x32_bf16 v[128:131], v[144:147], v[198:201], v[128:131]
	v_mfma_f32_16x16x32_bf16 v[132:135], v[186:189], v[198:201], v[132:135]
	v_mfma_f32_16x16x32_bf16 v[104:107], v[144:147], v[210:213], v[104:107]
	v_mfma_f32_16x16x32_bf16 v[108:111], v[186:189], v[210:213], v[108:111]
	v_mfma_f32_16x16x32_bf16 v[80:83], v[144:147], v[218:221], v[80:83]
	v_mfma_f32_16x16x32_bf16 v[84:87], v[186:189], v[218:221], v[84:87]
	v_mfma_f32_16x16x32_bf16 v[64:67], v[144:147], v[226:229], v[64:67]
	v_mfma_f32_16x16x32_bf16 v[68:71], v[186:189], v[226:229], v[68:71]
	v_mfma_f32_16x16x32_bf16 v[128:131], v[170:173], v[206:209], v[128:131]
	v_mfma_f32_16x16x32_bf16 v[132:135], v[190:193], v[206:209], v[132:135]
	v_mfma_f32_16x16x32_bf16 v[104:107], v[170:173], v[214:217], v[104:107]
	v_mfma_f32_16x16x32_bf16 v[108:111], v[190:193], v[214:217], v[108:111]
	v_mfma_f32_16x16x32_bf16 v[80:83], v[170:173], v[222:225], v[80:83]
	v_mfma_f32_16x16x32_bf16 v[84:87], v[190:193], v[222:225], v[84:87]
	v_mfma_f32_16x16x32_bf16 v[64:67], v[170:173], v[230:233], v[64:67]
	v_mfma_f32_16x16x32_bf16 v[68:71], v[190:193], v[230:233], v[68:71]
	s_setprio 0
	s_barrier
	s_add_i32 s44, s56, s91
	v_lshl_add_u64 v[194:195], s[84:85], 0, v[150:151]
	s_mov_b32 m0, s44
	ds_read_b128 v[198:201], v185 offset:16384
	ds_read_b128 v[206:209], v185 offset:17408
	ds_read_b128 v[210:213], v185 offset:18432
	ds_read_b128 v[214:217], v185 offset:19456
	ds_read_b128 v[218:221], v185 offset:20480
	ds_read_b128 v[222:225], v185 offset:21504
	ds_read_b128 v[226:229], v185 offset:22528
	ds_read_b128 v[230:233], v185 offset:23552
	global_load_lds_dwordx4 v[194:195], off
	s_add_i32 m0, s44, 0x2000
	s_add_u32 s44, s84, 0x40000
	v_lshl_add_u64 v[234:235], s[84:85], 0, v[154:155]
	s_addc_u32 s45, s85, 0
	s_add_i32 s90, s57, s91
	global_load_lds_dwordx4 v[234:235], off
	v_lshl_add_u64 v[236:237], s[44:45], 0, v[150:151]
	s_mov_b32 m0, s90
	v_lshl_add_u64 v[238:239], s[86:87], 0, v[152:153]
	global_load_lds_dwordx4 v[236:237], off
	v_lshl_add_u64 v[236:237], s[44:45], 0, v[154:155]
	s_add_i32 m0, s90, 0x2000
	s_nop 0
	global_load_lds_dwordx4 v[236:237], off
	v_lshl_add_u64 v[236:237], s[86:87], 0, v[148:149]
	s_mov_b32 m0, s92
	s_nop 0
	global_load_lds_dwordx4 v[236:237], off
	s_mov_b32 m0, s93
	s_nop 0
	global_load_lds_dwordx4 v[238:239], off
	s_waitcnt vmcnt(8)
	s_waitcnt lgkmcnt(0)
	s_barrier
	s_setprio 1
	s_waitcnt lgkmcnt(0)
	v_mfma_f32_16x16x32_bf16 v[60:63], v[96:99], v[198:201], v[60:63]
	v_mfma_f32_16x16x32_bf16 v[56:59], v[112:115], v[198:201], v[56:59]
	v_mfma_f32_16x16x32_bf16 v[44:47], v[96:99], v[210:213], v[44:47]
	v_mfma_f32_16x16x32_bf16 v[40:43], v[112:115], v[210:213], v[40:43]
	v_mfma_f32_16x16x32_bf16 v[28:31], v[96:99], v[218:221], v[28:31]
	v_mfma_f32_16x16x32_bf16 v[24:27], v[112:115], v[218:221], v[24:27]
	v_mfma_f32_16x16x32_bf16 v[12:15], v[96:99], v[226:229], v[12:15]
	v_mfma_f32_16x16x32_bf16 v[8:11], v[112:115], v[226:229], v[8:11]
	v_mfma_f32_16x16x32_bf16 v[60:63], v[100:103], v[206:209], v[60:63]
	v_mfma_f32_16x16x32_bf16 v[56:59], v[120:123], v[206:209], v[56:59]
	v_mfma_f32_16x16x32_bf16 v[44:47], v[100:103], v[214:217], v[44:47]
	v_mfma_f32_16x16x32_bf16 v[40:43], v[120:123], v[214:217], v[40:43]
	v_mfma_f32_16x16x32_bf16 v[28:31], v[100:103], v[222:225], v[28:31]
	v_mfma_f32_16x16x32_bf16 v[24:27], v[120:123], v[222:225], v[24:27]
	v_mfma_f32_16x16x32_bf16 v[12:15], v[100:103], v[230:233], v[12:15]
	v_mfma_f32_16x16x32_bf16 v[8:11], v[120:123], v[230:233], v[8:11]
	s_setprio 0
	s_setprio 1
	v_mfma_f32_16x16x32_bf16 v[48:51], v[144:147], v[198:201], v[48:51]
	v_mfma_f32_16x16x32_bf16 v[52:55], v[186:189], v[198:201], v[52:55]
	v_mfma_f32_16x16x32_bf16 v[32:35], v[144:147], v[210:213], v[32:35]
	v_mfma_f32_16x16x32_bf16 v[36:39], v[186:189], v[210:213], v[36:39]
	v_mfma_f32_16x16x32_bf16 v[16:19], v[144:147], v[218:221], v[16:19]
	v_mfma_f32_16x16x32_bf16 v[20:23], v[186:189], v[218:221], v[20:23]
	v_mfma_f32_16x16x32_bf16 v[4:7], v[144:147], v[226:229], v[4:7]
	v_mfma_f32_16x16x32_bf16 v[0:3], v[186:189], v[226:229], v[0:3]
	v_mfma_f32_16x16x32_bf16 v[48:51], v[170:173], v[206:209], v[48:51]
	v_mfma_f32_16x16x32_bf16 v[52:55], v[190:193], v[206:209], v[52:55]
	v_mfma_f32_16x16x32_bf16 v[32:35], v[170:173], v[214:217], v[32:35]
	v_mfma_f32_16x16x32_bf16 v[36:39], v[190:193], v[214:217], v[36:39]
	v_mfma_f32_16x16x32_bf16 v[16:19], v[170:173], v[222:225], v[16:19]
	v_mfma_f32_16x16x32_bf16 v[20:23], v[190:193], v[222:225], v[20:23]
	v_mfma_f32_16x16x32_bf16 v[4:7], v[170:173], v[230:233], v[4:7]
	v_mfma_f32_16x16x32_bf16 v[0:3], v[190:193], v[230:233], v[0:3]
	s_setprio 0
	s_barrier
	s_add_i32 s90, 0, 0x18000
	s_add_i32 s33, 0, 0x1c000
	v_add_u32_e32 v120, s90, v175
	v_add_u32_e32 v190, s33, v175
	ds_read_b128 v[96:99], v120
	ds_read_b128 v[100:103], v120 offset:1024
	ds_read_b128 v[112:115], v120 offset:2048
	ds_read_b128 v[120:123], v120 offset:3072
	ds_read_b128 v[144:147], v190
	ds_read_b128 v[170:173], v190 offset:1024
	ds_read_b128 v[186:189], v190 offset:2048
	ds_read_b128 v[190:193], v190 offset:3072
	s_add_u32 s44, s86, 0x40000
	s_addc_u32 s45, s87, 0
	s_mov_b32 m0, s94
	v_lshl_add_u64 v[240:241], s[44:45], 0, v[148:149]
	ds_read_b128 v[198:201], v185 offset:32768
	ds_read_b128 v[206:209], v185 offset:33792
	ds_read_b128 v[210:213], v185 offset:34816
	ds_read_b128 v[214:217], v185 offset:35840
	ds_read_b128 v[218:221], v185 offset:36864
	ds_read_b128 v[222:225], v185 offset:37888
	ds_read_b128 v[226:229], v185 offset:38912
	ds_read_b128 v[230:233], v185 offset:39936
	global_load_lds_dwordx4 v[240:241], off
	v_lshl_add_u64 v[240:241], s[44:45], 0, v[152:153]
	s_mov_b32 m0, s95
	s_nop 0
	global_load_lds_dwordx4 v[240:241], off
	s_waitcnt vmcnt(8)
	s_waitcnt lgkmcnt(0)
	s_barrier
	s_setprio 1
	s_waitcnt lgkmcnt(0)
	v_mfma_f32_16x16x32_bf16 v[140:143], v[96:99], v[198:201], v[140:143]
	v_mfma_f32_16x16x32_bf16 v[136:139], v[112:115], v[198:201], v[136:139]
	v_mfma_f32_16x16x32_bf16 v[124:127], v[96:99], v[210:213], v[124:127]
	v_mfma_f32_16x16x32_bf16 v[116:119], v[112:115], v[210:213], v[116:119]
	v_mfma_f32_16x16x32_bf16 v[92:95], v[96:99], v[218:221], v[92:95]
	v_mfma_f32_16x16x32_bf16 v[88:91], v[112:115], v[218:221], v[88:91]
	v_mfma_f32_16x16x32_bf16 v[76:79], v[96:99], v[226:229], v[76:79]
	v_mfma_f32_16x16x32_bf16 v[72:75], v[112:115], v[226:229], v[72:75]
	v_mfma_f32_16x16x32_bf16 v[140:143], v[100:103], v[206:209], v[140:143]
	v_mfma_f32_16x16x32_bf16 v[136:139], v[120:123], v[206:209], v[136:139]
	v_mfma_f32_16x16x32_bf16 v[124:127], v[100:103], v[214:217], v[124:127]
	v_mfma_f32_16x16x32_bf16 v[116:119], v[120:123], v[214:217], v[116:119]
	v_mfma_f32_16x16x32_bf16 v[92:95], v[100:103], v[222:225], v[92:95]
	v_mfma_f32_16x16x32_bf16 v[88:91], v[120:123], v[222:225], v[88:91]
	v_mfma_f32_16x16x32_bf16 v[76:79], v[100:103], v[230:233], v[76:79]
	v_mfma_f32_16x16x32_bf16 v[72:75], v[120:123], v[230:233], v[72:75]
	s_setprio 0
	s_setprio 1
	v_mfma_f32_16x16x32_bf16 v[128:131], v[144:147], v[198:201], v[128:131]
	v_mfma_f32_16x16x32_bf16 v[132:135], v[186:189], v[198:201], v[132:135]
	v_mfma_f32_16x16x32_bf16 v[104:107], v[144:147], v[210:213], v[104:107]
	v_mfma_f32_16x16x32_bf16 v[108:111], v[186:189], v[210:213], v[108:111]
	v_mfma_f32_16x16x32_bf16 v[80:83], v[144:147], v[218:221], v[80:83]
	v_mfma_f32_16x16x32_bf16 v[84:87], v[186:189], v[218:221], v[84:87]
	v_mfma_f32_16x16x32_bf16 v[64:67], v[144:147], v[226:229], v[64:67]
	v_mfma_f32_16x16x32_bf16 v[68:71], v[186:189], v[226:229], v[68:71]
	v_mfma_f32_16x16x32_bf16 v[128:131], v[170:173], v[206:209], v[128:131]
	v_mfma_f32_16x16x32_bf16 v[132:135], v[190:193], v[206:209], v[132:135]
	v_mfma_f32_16x16x32_bf16 v[104:107], v[170:173], v[214:217], v[104:107]
	v_mfma_f32_16x16x32_bf16 v[108:111], v[190:193], v[214:217], v[108:111]
	v_mfma_f32_16x16x32_bf16 v[80:83], v[170:173], v[222:225], v[80:83]
	v_mfma_f32_16x16x32_bf16 v[84:87], v[190:193], v[222:225], v[84:87]
	v_mfma_f32_16x16x32_bf16 v[64:67], v[170:173], v[230:233], v[64:67]
	v_mfma_f32_16x16x32_bf16 v[68:71], v[190:193], v[230:233], v[68:71]
	s_setprio 0
	s_barrier
	s_add_i32 s44, s90, s91
	v_lshl_add_u64 v[194:195], v[194:195], 0, s[62:63]
	s_mov_b32 m0, s44
	ds_read_b128 v[198:201], v185 offset:49152
	ds_read_b128 v[206:209], v185 offset:50176
	ds_read_b128 v[210:213], v185 offset:51200
	ds_read_b128 v[214:217], v185 offset:52224
	ds_read_b128 v[218:221], v185 offset:53248
	ds_read_b128 v[222:225], v185 offset:54272
	ds_read_b128 v[226:229], v185 offset:55296
	ds_read_b128 v[230:233], v185 offset:56320
	global_load_lds_dwordx4 v[194:195], off
	s_add_i32 m0, s44, 0x2000
	s_add_u32 s44, s84, 0x40080
	v_lshl_add_u64 v[194:195], v[234:235], 0, s[62:63]
	s_addc_u32 s45, s85, 0
	s_add_i32 s33, s33, s91
	global_load_lds_dwordx4 v[194:195], off
	v_lshl_add_u64 v[194:195], s[44:45], 0, v[150:151]
	s_mov_b32 m0, s33
	s_nop 0
	global_load_lds_dwordx4 v[194:195], off
	v_lshl_add_u64 v[194:195], s[44:45], 0, v[154:155]
	s_add_i32 m0, s33, 0x2000
	s_nop 0
	global_load_lds_dwordx4 v[194:195], off
	v_lshl_add_u64 v[194:195], v[236:237], 0, s[62:63]
	s_mov_b32 m0, s97
	s_nop 0
	global_load_lds_dwordx4 v[194:195], off
	v_lshl_add_u64 v[194:195], v[238:239], 0, s[62:63]
	s_mov_b32 m0, s98
	s_nop 0
	global_load_lds_dwordx4 v[194:195], off
	s_waitcnt vmcnt(8)
	s_waitcnt lgkmcnt(0)
	s_barrier
	s_setprio 1
	s_waitcnt lgkmcnt(0)
	v_mfma_f32_16x16x32_bf16 v[60:63], v[96:99], v[198:201], v[60:63]
	v_mfma_f32_16x16x32_bf16 v[56:59], v[112:115], v[198:201], v[56:59]
	v_mfma_f32_16x16x32_bf16 v[44:47], v[96:99], v[210:213], v[44:47]
	v_mfma_f32_16x16x32_bf16 v[40:43], v[112:115], v[210:213], v[40:43]
	v_mfma_f32_16x16x32_bf16 v[28:31], v[96:99], v[218:221], v[28:31]
	v_mfma_f32_16x16x32_bf16 v[24:27], v[112:115], v[218:221], v[24:27]
	v_mfma_f32_16x16x32_bf16 v[12:15], v[96:99], v[226:229], v[12:15]
	v_mfma_f32_16x16x32_bf16 v[8:11], v[112:115], v[226:229], v[8:11]
	v_mfma_f32_16x16x32_bf16 v[60:63], v[100:103], v[206:209], v[60:63]
	v_mfma_f32_16x16x32_bf16 v[56:59], v[120:123], v[206:209], v[56:59]
	v_mfma_f32_16x16x32_bf16 v[44:47], v[100:103], v[214:217], v[44:47]
	v_mfma_f32_16x16x32_bf16 v[40:43], v[120:123], v[214:217], v[40:43]
	v_mfma_f32_16x16x32_bf16 v[28:31], v[100:103], v[222:225], v[28:31]
	v_mfma_f32_16x16x32_bf16 v[24:27], v[120:123], v[222:225], v[24:27]
	v_mfma_f32_16x16x32_bf16 v[12:15], v[100:103], v[230:233], v[12:15]
	v_mfma_f32_16x16x32_bf16 v[8:11], v[120:123], v[230:233], v[8:11]
	s_setprio 0
	s_setprio 1
	v_mfma_f32_16x16x32_bf16 v[48:51], v[144:147], v[198:201], v[48:51]
	v_mfma_f32_16x16x32_bf16 v[52:55], v[186:189], v[198:201], v[52:55]
	v_mfma_f32_16x16x32_bf16 v[32:35], v[144:147], v[210:213], v[32:35]
	v_mfma_f32_16x16x32_bf16 v[36:39], v[186:189], v[210:213], v[36:39]
	v_mfma_f32_16x16x32_bf16 v[16:19], v[144:147], v[218:221], v[16:19]
	v_mfma_f32_16x16x32_bf16 v[20:23], v[186:189], v[218:221], v[20:23]
	v_mfma_f32_16x16x32_bf16 v[4:7], v[144:147], v[226:229], v[4:7]
	v_mfma_f32_16x16x32_bf16 v[0:3], v[186:189], v[226:229], v[0:3]
	v_mfma_f32_16x16x32_bf16 v[48:51], v[170:173], v[206:209], v[48:51]
	v_mfma_f32_16x16x32_bf16 v[52:55], v[190:193], v[206:209], v[52:55]
	v_mfma_f32_16x16x32_bf16 v[32:35], v[170:173], v[214:217], v[32:35]
	v_mfma_f32_16x16x32_bf16 v[36:39], v[190:193], v[214:217], v[36:39]
	v_mfma_f32_16x16x32_bf16 v[16:19], v[170:173], v[222:225], v[16:19]
	v_mfma_f32_16x16x32_bf16 v[20:23], v[190:193], v[222:225], v[20:23]
	v_mfma_f32_16x16x32_bf16 v[4:7], v[170:173], v[230:233], v[4:7]
	v_mfma_f32_16x16x32_bf16 v[0:3], v[190:193], v[230:233], v[0:3]
	s_setprio 0
	s_add_i32 s89, s89, 2
	s_add_u32 s0, s0, 0x100
	s_addc_u32 s1, s1, 0
	s_add_u32 s14, s14, 0x100
	s_addc_u32 s15, s15, 0
	s_cmp_gt_u32 s89, 13
	s_barrier
	s_cbranch_scc0 .LBB0_143
	s_and_b64 vcc, exec, s[64:65]
	s_cbranch_vccz .LBB0_146
	s_barrier

.LBB0_259:
	ds_read_b128 v[128:131], v171
	ds_read_b128 v[132:135], v171 offset:1024
	ds_read_b128 v[136:139], v171 offset:2048
	ds_read_b128 v[156:159], v171 offset:3072
	ds_read_b128 v[160:163], v172
	ds_read_b128 v[164:167], v172 offset:1024
	ds_read_b128 v[176:179], v172 offset:2048
	ds_read_b128 v[180:183], v172 offset:3072
	s_add_u32 s16, s12, 0xfffc0080
	s_addc_u32 s17, s13, -1
	s_cmp_eq_u32 s57, 12
	s_cselect_b32 s19, s1, s17
	s_cselect_b32 s18, s20, s16
	s_cselect_b32 s17, s21, s15
	s_cselect_b32 s16, s56, s14
	v_lshl_add_u64 v[222:223], s[12:13], 0, v[148:149]
	s_add_i32 m0, s83, 0xc000
	ds_read_b128 v[184:187], v173
	ds_read_b128 v[188:191], v173 offset:1024
	ds_read_b128 v[192:195], v173 offset:2048
	ds_read_b128 v[198:201], v173 offset:3072
	ds_read_b128 v[206:209], v173 offset:4096
	ds_read_b128 v[210:213], v173 offset:5120
	ds_read_b128 v[214:217], v173 offset:6144
	ds_read_b128 v[218:221], v173 offset:7168
	global_load_lds_dwordx4 v[222:223], off
	v_lshl_add_u64 v[222:223], s[12:13], 0, v[150:151]
	s_add_i32 m0, s83, 0xe000
	s_nop 0
	global_load_lds_dwordx4 v[222:223], off
	s_waitcnt vmcnt(8)
	s_waitcnt lgkmcnt(0)
	s_barrier
	s_setprio 1
	s_waitcnt lgkmcnt(0)
	v_mfma_f32_16x16x32_bf16 v[124:127], v[128:131], v[184:187], v[124:127]
	v_mfma_f32_16x16x32_bf16 v[120:123], v[136:139], v[184:187], v[120:123]
	v_mfma_f32_16x16x32_bf16 v[108:111], v[128:131], v[192:195], v[108:111]
	v_mfma_f32_16x16x32_bf16 v[104:107], v[136:139], v[192:195], v[104:107]
	v_mfma_f32_16x16x32_bf16 v[92:95], v[128:131], v[206:209], v[92:95]
	v_mfma_f32_16x16x32_bf16 v[88:91], v[136:139], v[206:209], v[88:91]
	v_mfma_f32_16x16x32_bf16 v[76:79], v[128:131], v[214:217], v[76:79]
	v_mfma_f32_16x16x32_bf16 v[72:75], v[136:139], v[214:217], v[72:75]
	v_mfma_f32_16x16x32_bf16 v[124:127], v[132:135], v[188:191], v[124:127]
	v_mfma_f32_16x16x32_bf16 v[120:123], v[156:159], v[188:191], v[120:123]
	v_mfma_f32_16x16x32_bf16 v[108:111], v[132:135], v[198:201], v[108:111]
	v_mfma_f32_16x16x32_bf16 v[104:107], v[156:159], v[198:201], v[104:107]
	v_mfma_f32_16x16x32_bf16 v[92:95], v[132:135], v[210:213], v[92:95]
	v_mfma_f32_16x16x32_bf16 v[88:91], v[156:159], v[210:213], v[88:91]
	v_mfma_f32_16x16x32_bf16 v[76:79], v[132:135], v[218:221], v[76:79]
	v_mfma_f32_16x16x32_bf16 v[72:75], v[156:159], v[218:221], v[72:75]
	s_setprio 0
	s_setprio 1
	v_mfma_f32_16x16x32_bf16 v[116:119], v[160:163], v[184:187], v[116:119]
	v_mfma_f32_16x16x32_bf16 v[112:115], v[176:179], v[184:187], v[112:115]
	v_mfma_f32_16x16x32_bf16 v[100:103], v[160:163], v[192:195], v[100:103]
	v_mfma_f32_16x16x32_bf16 v[96:99], v[176:179], v[192:195], v[96:99]
	v_mfma_f32_16x16x32_bf16 v[84:87], v[160:163], v[206:209], v[84:87]
	v_mfma_f32_16x16x32_bf16 v[80:83], v[176:179], v[206:209], v[80:83]
	v_mfma_f32_16x16x32_bf16 v[68:71], v[160:163], v[214:217], v[68:71]
	v_mfma_f32_16x16x32_bf16 v[64:67], v[176:179], v[214:217], v[64:67]
	v_mfma_f32_16x16x32_bf16 v[116:119], v[164:167], v[188:191], v[116:119]
	v_mfma_f32_16x16x32_bf16 v[112:115], v[180:183], v[188:191], v[112:115]
	v_mfma_f32_16x16x32_bf16 v[100:103], v[164:167], v[198:201], v[100:103]
	v_mfma_f32_16x16x32_bf16 v[96:99], v[180:183], v[198:201], v[96:99]
	v_mfma_f32_16x16x32_bf16 v[84:87], v[164:167], v[210:213], v[84:87]
	v_mfma_f32_16x16x32_bf16 v[80:83], v[180:183], v[210:213], v[80:83]
	v_mfma_f32_16x16x32_bf16 v[68:71], v[164:167], v[218:221], v[68:71]
	v_mfma_f32_16x16x32_bf16 v[64:67], v[180:183], v[218:221], v[64:67]
	s_setprio 0
	s_barrier
	s_add_i32 s33, s93, s82
	v_lshl_add_u64 v[222:223], s[16:17], 0, v[142:143]
	s_mov_b32 m0, s33
	ds_read_b128 v[184:187], v173 offset:16384
	ds_read_b128 v[188:191], v173 offset:17408
	ds_read_b128 v[192:195], v173 offset:18432
	ds_read_b128 v[198:201], v173 offset:19456
	ds_read_b128 v[206:209], v173 offset:20480
	ds_read_b128 v[210:213], v173 offset:21504
	ds_read_b128 v[214:217], v173 offset:22528
	ds_read_b128 v[218:221], v173 offset:23552
	global_load_lds_dwordx4 v[222:223], off
	s_add_i32 m0, s33, 0x2000
	s_add_u32 s44, s16, 0x40000
	v_lshl_add_u64 v[224:225], s[16:17], 0, v[146:147]
	s_addc_u32 s45, s17, 0
	s_add_i32 s33, s94, s82
	global_load_lds_dwordx4 v[224:225], off
	v_lshl_add_u64 v[226:227], s[44:45], 0, v[142:143]
	s_mov_b32 m0, s33
	v_lshl_add_u64 v[228:229], s[18:19], 0, v[144:145]
	global_load_lds_dwordx4 v[226:227], off
	v_lshl_add_u64 v[226:227], s[44:45], 0, v[146:147]
	s_add_i32 m0, s33, 0x2000
	s_nop 0
	global_load_lds_dwordx4 v[226:227], off
	v_lshl_add_u64 v[226:227], s[18:19], 0, v[140:141]
	s_mov_b32 m0, s83
	s_nop 0
	global_load_lds_dwordx4 v[226:227], off
	s_mov_b32 m0, s84
	s_nop 0
	global_load_lds_dwordx4 v[228:229], off
	s_waitcnt vmcnt(8)
	s_waitcnt lgkmcnt(0)
	s_barrier
	s_setprio 1
	s_waitcnt lgkmcnt(0)
	v_mfma_f32_16x16x32_bf16 v[60:63], v[128:131], v[184:187], v[60:63]
	v_mfma_f32_16x16x32_bf16 v[56:59], v[136:139], v[184:187], v[56:59]
	v_mfma_f32_16x16x32_bf16 v[44:47], v[128:131], v[192:195], v[44:47]
	v_mfma_f32_16x16x32_bf16 v[40:43], v[136:139], v[192:195], v[40:43]
	v_mfma_f32_16x16x32_bf16 v[28:31], v[128:131], v[206:209], v[28:31]
	v_mfma_f32_16x16x32_bf16 v[24:27], v[136:139], v[206:209], v[24:27]
	v_mfma_f32_16x16x32_bf16 v[12:15], v[128:131], v[214:217], v[12:15]
	v_mfma_f32_16x16x32_bf16 v[8:11], v[136:139], v[214:217], v[8:11]
	v_mfma_f32_16x16x32_bf16 v[60:63], v[132:135], v[188:191], v[60:63]
	v_mfma_f32_16x16x32_bf16 v[56:59], v[156:159], v[188:191], v[56:59]
	v_mfma_f32_16x16x32_bf16 v[44:47], v[132:135], v[198:201], v[44:47]
	v_mfma_f32_16x16x32_bf16 v[40:43], v[156:159], v[198:201], v[40:43]
	v_mfma_f32_16x16x32_bf16 v[28:31], v[132:135], v[210:213], v[28:31]
	v_mfma_f32_16x16x32_bf16 v[24:27], v[156:159], v[210:213], v[24:27]
	v_mfma_f32_16x16x32_bf16 v[12:15], v[132:135], v[218:221], v[12:15]
	v_mfma_f32_16x16x32_bf16 v[8:11], v[156:159], v[218:221], v[8:11]
	s_setprio 0
	s_setprio 1
	v_mfma_f32_16x16x32_bf16 v[52:55], v[160:163], v[184:187], v[52:55]
	v_mfma_f32_16x16x32_bf16 v[48:51], v[176:179], v[184:187], v[48:51]
	v_mfma_f32_16x16x32_bf16 v[36:39], v[160:163], v[192:195], v[36:39]
	v_mfma_f32_16x16x32_bf16 v[32:35], v[176:179], v[192:195], v[32:35]
	v_mfma_f32_16x16x32_bf16 v[20:23], v[160:163], v[206:209], v[20:23]
	v_mfma_f32_16x16x32_bf16 v[16:19], v[176:179], v[206:209], v[16:19]
	v_mfma_f32_16x16x32_bf16 v[4:7], v[160:163], v[214:217], v[4:7]
	v_mfma_f32_16x16x32_bf16 v[0:3], v[176:179], v[214:217], v[0:3]
	v_mfma_f32_16x16x32_bf16 v[52:55], v[164:167], v[188:191], v[52:55]
	v_mfma_f32_16x16x32_bf16 v[48:51], v[180:183], v[188:191], v[48:51]
	v_mfma_f32_16x16x32_bf16 v[36:39], v[164:167], v[198:201], v[36:39]
	v_mfma_f32_16x16x32_bf16 v[32:35], v[180:183], v[198:201], v[32:35]
	v_mfma_f32_16x16x32_bf16 v[20:23], v[164:167], v[210:213], v[20:23]
	v_mfma_f32_16x16x32_bf16 v[16:19], v[180:183], v[210:213], v[16:19]
	v_mfma_f32_16x16x32_bf16 v[4:7], v[164:167], v[218:221], v[4:7]
	v_mfma_f32_16x16x32_bf16 v[0:3], v[180:183], v[218:221], v[0:3]
	s_setprio 0
	s_barrier
	s_add_i32 s33, 0, 0x18000
	s_add_i32 s44, 0, 0x1c000
	v_add_u32_e32 v156, s33, v169
	v_add_u32_e32 v175, s44, v169
	ds_read_b128 v[128:131], v156
	ds_read_b128 v[132:135], v156 offset:1024
	ds_read_b128 v[136:139], v156 offset:2048
	ds_read_b128 v[156:159], v156 offset:3072
	ds_read_b128 v[160:163], v175
	ds_read_b128 v[164:167], v175 offset:1024
	ds_read_b128 v[176:179], v175 offset:2048
	ds_read_b128 v[180:183], v175 offset:3072
	s_add_u32 s18, s18, 0x40000
	s_addc_u32 s19, s19, 0
	s_mov_b32 m0, s85
	v_lshl_add_u64 v[230:231], s[18:19], 0, v[140:141]
	ds_read_b128 v[184:187], v173 offset:32768
	ds_read_b128 v[188:191], v173 offset:33792
	ds_read_b128 v[192:195], v173 offset:34816
	ds_read_b128 v[198:201], v173 offset:35840
	ds_read_b128 v[206:209], v173 offset:36864
	ds_read_b128 v[210:213], v173 offset:37888
	ds_read_b128 v[214:217], v173 offset:38912
	ds_read_b128 v[218:221], v173 offset:39936
	global_load_lds_dwordx4 v[230:231], off
	v_lshl_add_u64 v[230:231], s[18:19], 0, v[144:145]
	s_mov_b32 m0, s86
	s_nop 0
	global_load_lds_dwordx4 v[230:231], off
	s_waitcnt vmcnt(8)
	s_waitcnt lgkmcnt(0)
	s_barrier
	s_setprio 1
	s_waitcnt lgkmcnt(0)
	v_mfma_f32_16x16x32_bf16 v[124:127], v[128:131], v[184:187], v[124:127]
	v_mfma_f32_16x16x32_bf16 v[120:123], v[136:139], v[184:187], v[120:123]
	v_mfma_f32_16x16x32_bf16 v[108:111], v[128:131], v[192:195], v[108:111]
	v_mfma_f32_16x16x32_bf16 v[104:107], v[136:139], v[192:195], v[104:107]
	v_mfma_f32_16x16x32_bf16 v[92:95], v[128:131], v[206:209], v[92:95]
	v_mfma_f32_16x16x32_bf16 v[88:91], v[136:139], v[206:209], v[88:91]
	v_mfma_f32_16x16x32_bf16 v[76:79], v[128:131], v[214:217], v[76:79]
	v_mfma_f32_16x16x32_bf16 v[72:75], v[136:139], v[214:217], v[72:75]
	v_mfma_f32_16x16x32_bf16 v[124:127], v[132:135], v[188:191], v[124:127]
	v_mfma_f32_16x16x32_bf16 v[120:123], v[156:159], v[188:191], v[120:123]
	v_mfma_f32_16x16x32_bf16 v[108:111], v[132:135], v[198:201], v[108:111]
	v_mfma_f32_16x16x32_bf16 v[104:107], v[156:159], v[198:201], v[104:107]
	v_mfma_f32_16x16x32_bf16 v[92:95], v[132:135], v[210:213], v[92:95]
	v_mfma_f32_16x16x32_bf16 v[88:91], v[156:159], v[210:213], v[88:91]
	v_mfma_f32_16x16x32_bf16 v[76:79], v[132:135], v[218:221], v[76:79]
	v_mfma_f32_16x16x32_bf16 v[72:75], v[156:159], v[218:221], v[72:75]
	s_setprio 0
	s_setprio 1
	v_mfma_f32_16x16x32_bf16 v[116:119], v[160:163], v[184:187], v[116:119]
	v_mfma_f32_16x16x32_bf16 v[112:115], v[176:179], v[184:187], v[112:115]
	v_mfma_f32_16x16x32_bf16 v[100:103], v[160:163], v[192:195], v[100:103]
	v_mfma_f32_16x16x32_bf16 v[96:99], v[176:179], v[192:195], v[96:99]
	v_mfma_f32_16x16x32_bf16 v[84:87], v[160:163], v[206:209], v[84:87]
	v_mfma_f32_16x16x32_bf16 v[80:83], v[176:179], v[206:209], v[80:83]
	v_mfma_f32_16x16x32_bf16 v[68:71], v[160:163], v[214:217], v[68:71]
	v_mfma_f32_16x16x32_bf16 v[64:67], v[176:179], v[214:217], v[64:67]
	v_mfma_f32_16x16x32_bf16 v[116:119], v[164:167], v[188:191], v[116:119]
	v_mfma_f32_16x16x32_bf16 v[112:115], v[180:183], v[188:191], v[112:115]
	v_mfma_f32_16x16x32_bf16 v[100:103], v[164:167], v[198:201], v[100:103]
	v_mfma_f32_16x16x32_bf16 v[96:99], v[180:183], v[198:201], v[96:99]
	v_mfma_f32_16x16x32_bf16 v[84:87], v[164:167], v[210:213], v[84:87]
	v_mfma_f32_16x16x32_bf16 v[80:83], v[180:183], v[210:213], v[80:83]
	v_mfma_f32_16x16x32_bf16 v[68:71], v[164:167], v[218:221], v[68:71]
	v_mfma_f32_16x16x32_bf16 v[64:67], v[180:183], v[218:221], v[64:67]
	s_setprio 0
	s_barrier
	s_add_i32 s18, s33, s82
	v_lshl_add_u64 v[222:223], v[222:223], 0, s[68:69]
	s_mov_b32 m0, s18
	ds_read_b128 v[184:187], v173 offset:49152
	ds_read_b128 v[188:191], v173 offset:50176
	ds_read_b128 v[192:195], v173 offset:51200
	ds_read_b128 v[198:201], v173 offset:52224
	ds_read_b128 v[206:209], v173 offset:53248
	ds_read_b128 v[210:213], v173 offset:54272
	ds_read_b128 v[214:217], v173 offset:55296
	ds_read_b128 v[218:221], v173 offset:56320
	global_load_lds_dwordx4 v[222:223], off
	s_add_i32 m0, s18, 0x2000
	s_add_u32 s16, s16, 0x40080
	v_lshl_add_u64 v[222:223], v[224:225], 0, s[68:69]
	s_addc_u32 s17, s17, 0
	s_add_i32 s18, s44, s82
	global_load_lds_dwordx4 v[222:223], off
	v_lshl_add_u64 v[222:223], s[16:17], 0, v[142:143]
	s_mov_b32 m0, s18
	s_nop 0
	global_load_lds_dwordx4 v[222:223], off
	v_lshl_add_u64 v[222:223], s[16:17], 0, v[146:147]
	s_add_i32 m0, s18, 0x2000
	s_nop 0
	global_load_lds_dwordx4 v[222:223], off
	v_lshl_add_u64 v[222:223], v[226:227], 0, s[68:69]
	s_mov_b32 m0, s91
	s_nop 0
	global_load_lds_dwordx4 v[222:223], off
	v_lshl_add_u64 v[222:223], v[228:229], 0, s[68:69]
	s_mov_b32 m0, s92
	s_nop 0
	global_load_lds_dwordx4 v[222:223], off
	s_waitcnt vmcnt(8)
	s_waitcnt lgkmcnt(0)
	s_barrier
	s_setprio 1
	s_waitcnt lgkmcnt(0)
	v_mfma_f32_16x16x32_bf16 v[60:63], v[128:131], v[184:187], v[60:63]
	v_mfma_f32_16x16x32_bf16 v[56:59], v[136:139], v[184:187], v[56:59]
	v_mfma_f32_16x16x32_bf16 v[44:47], v[128:131], v[192:195], v[44:47]
	v_mfma_f32_16x16x32_bf16 v[40:43], v[136:139], v[192:195], v[40:43]
	v_mfma_f32_16x16x32_bf16 v[28:31], v[128:131], v[206:209], v[28:31]
	v_mfma_f32_16x16x32_bf16 v[24:27], v[136:139], v[206:209], v[24:27]
	v_mfma_f32_16x16x32_bf16 v[12:15], v[128:131], v[214:217], v[12:15]
	v_mfma_f32_16x16x32_bf16 v[8:11], v[136:139], v[214:217], v[8:11]
	v_mfma_f32_16x16x32_bf16 v[60:63], v[132:135], v[188:191], v[60:63]
	v_mfma_f32_16x16x32_bf16 v[56:59], v[156:159], v[188:191], v[56:59]
	v_mfma_f32_16x16x32_bf16 v[44:47], v[132:135], v[198:201], v[44:47]
	v_mfma_f32_16x16x32_bf16 v[40:43], v[156:159], v[198:201], v[40:43]
	v_mfma_f32_16x16x32_bf16 v[28:31], v[132:135], v[210:213], v[28:31]
	v_mfma_f32_16x16x32_bf16 v[24:27], v[156:159], v[210:213], v[24:27]
	v_mfma_f32_16x16x32_bf16 v[12:15], v[132:135], v[218:221], v[12:15]
	v_mfma_f32_16x16x32_bf16 v[8:11], v[156:159], v[218:221], v[8:11]
	s_setprio 0
	s_setprio 1
	v_mfma_f32_16x16x32_bf16 v[52:55], v[160:163], v[184:187], v[52:55]
	v_mfma_f32_16x16x32_bf16 v[48:51], v[176:179], v[184:187], v[48:51]
	v_mfma_f32_16x16x32_bf16 v[36:39], v[160:163], v[192:195], v[36:39]
	v_mfma_f32_16x16x32_bf16 v[32:35], v[176:179], v[192:195], v[32:35]
	v_mfma_f32_16x16x32_bf16 v[20:23], v[160:163], v[206:209], v[20:23]
	v_mfma_f32_16x16x32_bf16 v[16:19], v[176:179], v[206:209], v[16:19]
	v_mfma_f32_16x16x32_bf16 v[4:7], v[160:163], v[214:217], v[4:7]
	v_mfma_f32_16x16x32_bf16 v[0:3], v[176:179], v[214:217], v[0:3]
	v_mfma_f32_16x16x32_bf16 v[52:55], v[164:167], v[188:191], v[52:55]
	v_mfma_f32_16x16x32_bf16 v[48:51], v[180:183], v[188:191], v[48:51]
	v_mfma_f32_16x16x32_bf16 v[36:39], v[164:167], v[198:201], v[36:39]
	v_mfma_f32_16x16x32_bf16 v[32:35], v[180:183], v[198:201], v[32:35]
	v_mfma_f32_16x16x32_bf16 v[20:23], v[164:167], v[210:213], v[20:23]
	v_mfma_f32_16x16x32_bf16 v[16:19], v[180:183], v[210:213], v[16:19]
	v_mfma_f32_16x16x32_bf16 v[4:7], v[164:167], v[218:221], v[4:7]
	v_mfma_f32_16x16x32_bf16 v[0:3], v[180:183], v[218:221], v[0:3]
	s_setprio 0
	s_add_i32 s57, s57, 2
	s_add_u32 s12, s12, 0x100
	s_addc_u32 s13, s13, 0
	s_add_u32 s14, s14, 0x100
	s_addc_u32 s15, s15, 0
	s_cmp_gt_u32 s57, 13
	s_barrier
	s_cbranch_scc0 .LBB0_259
	s_and_b64 vcc, exec, s[70:71]
	s_cbranch_vccz .LBB0_262
	s_barrier

.LBB0_374:
	ds_read_b128 v[32:35], v208
	ds_read_b128 v[36:39], v208 offset:1024
	ds_read_b128 v[40:43], v208 offset:2048
	ds_read_b128 v[44:47], v208 offset:3072
	ds_read_b128 v[144:147], v209
	ds_read_b128 v[148:151], v209 offset:1024
	ds_read_b128 v[152:155], v209 offset:2048
	ds_read_b128 v[156:159], v209 offset:3072
	s_add_u32 s33, s68, 0xfffc0080
	s_addc_u32 s57, s69, -1
	s_cmp_eq_u32 s56, 12
	s_cselect_b32 s73, s11, s57
	s_cselect_b32 s72, s13, s33
	s_cselect_b32 s71, s21, s15
	s_cselect_b32 s70, s23, s14
	v_lshl_add_u64 v[194:195], s[68:69], 0, v[174:175]
	s_add_i32 m0, s77, 0xc000
	ds_read_b128 v[182:185], v210
	ds_read_b128 v[186:189], v210 offset:1024
	ds_read_b128 v[190:193], v210 offset:2048
	ds_read_b128 v[198:201], v210 offset:3072
	ds_read_b128 v[214:217], v210 offset:4096
	ds_read_b128 v[218:221], v210 offset:5120
	ds_read_b128 v[222:225], v210 offset:6144
	ds_read_b128 v[226:229], v210 offset:7168
	global_load_lds_dwordx4 v[194:195], off
	v_lshl_add_u64 v[194:195], s[68:69], 0, v[176:177]
	s_add_i32 m0, s77, 0xe000
	s_nop 0
	global_load_lds_dwordx4 v[194:195], off
	s_waitcnt vmcnt(8)
	s_waitcnt lgkmcnt(0)
	s_barrier
	s_setprio 1
	s_waitcnt lgkmcnt(0)
	v_mfma_f32_16x16x32_bf16 v[140:143], v[32:35], v[182:185], v[140:143]
	v_mfma_f32_16x16x32_bf16 v[136:139], v[40:43], v[182:185], v[136:139]
	v_mfma_f32_16x16x32_bf16 v[124:127], v[32:35], v[190:193], v[124:127]
	v_mfma_f32_16x16x32_bf16 v[120:123], v[40:43], v[190:193], v[120:123]
	v_mfma_f32_16x16x32_bf16 v[108:111], v[32:35], v[214:217], v[108:111]
	v_mfma_f32_16x16x32_bf16 v[104:107], v[40:43], v[214:217], v[104:107]
	v_mfma_f32_16x16x32_bf16 v[92:95], v[32:35], v[222:225], v[92:95]
	v_mfma_f32_16x16x32_bf16 v[88:91], v[40:43], v[222:225], v[88:91]
	v_mfma_f32_16x16x32_bf16 v[140:143], v[36:39], v[186:189], v[140:143]
	v_mfma_f32_16x16x32_bf16 v[136:139], v[44:47], v[186:189], v[136:139]
	v_mfma_f32_16x16x32_bf16 v[124:127], v[36:39], v[198:201], v[124:127]
	v_mfma_f32_16x16x32_bf16 v[120:123], v[44:47], v[198:201], v[120:123]
	v_mfma_f32_16x16x32_bf16 v[108:111], v[36:39], v[218:221], v[108:111]
	v_mfma_f32_16x16x32_bf16 v[104:107], v[44:47], v[218:221], v[104:107]
	v_mfma_f32_16x16x32_bf16 v[92:95], v[36:39], v[226:229], v[92:95]
	v_mfma_f32_16x16x32_bf16 v[88:91], v[44:47], v[226:229], v[88:91]
	s_setprio 0
	s_setprio 1
	v_mfma_f32_16x16x32_bf16 v[132:135], v[144:147], v[182:185], v[132:135]
	v_mfma_f32_16x16x32_bf16 v[128:131], v[152:155], v[182:185], v[128:131]
	v_mfma_f32_16x16x32_bf16 v[116:119], v[144:147], v[190:193], v[116:119]
	v_mfma_f32_16x16x32_bf16 v[112:115], v[152:155], v[190:193], v[112:115]
	v_mfma_f32_16x16x32_bf16 v[100:103], v[144:147], v[214:217], v[100:103]
	v_mfma_f32_16x16x32_bf16 v[96:99], v[152:155], v[214:217], v[96:99]
	v_mfma_f32_16x16x32_bf16 v[84:87], v[144:147], v[222:225], v[84:87]
	v_mfma_f32_16x16x32_bf16 v[80:83], v[152:155], v[222:225], v[80:83]
	v_mfma_f32_16x16x32_bf16 v[132:135], v[148:151], v[186:189], v[132:135]
	v_mfma_f32_16x16x32_bf16 v[128:131], v[156:159], v[186:189], v[128:131]
	v_mfma_f32_16x16x32_bf16 v[116:119], v[148:151], v[198:201], v[116:119]
	v_mfma_f32_16x16x32_bf16 v[112:115], v[156:159], v[198:201], v[112:115]
	v_mfma_f32_16x16x32_bf16 v[100:103], v[148:151], v[218:221], v[100:103]
	v_mfma_f32_16x16x32_bf16 v[96:99], v[156:159], v[218:221], v[96:99]
	v_mfma_f32_16x16x32_bf16 v[84:87], v[148:151], v[226:229], v[84:87]
	v_mfma_f32_16x16x32_bf16 v[80:83], v[156:159], v[226:229], v[80:83]
	s_setprio 0
	s_barrier
	s_add_i32 s33, s87, s76
	v_lshl_add_u64 v[194:195], s[70:71], 0, v[162:163]
	s_mov_b32 m0, s33
	ds_read_b128 v[182:185], v210 offset:16384
	ds_read_b128 v[186:189], v210 offset:17408
	ds_read_b128 v[190:193], v210 offset:18432
	ds_read_b128 v[198:201], v210 offset:19456
	ds_read_b128 v[214:217], v210 offset:20480
	ds_read_b128 v[218:221], v210 offset:21504
	ds_read_b128 v[222:225], v210 offset:22528
	ds_read_b128 v[226:229], v210 offset:23552
	global_load_lds_dwordx4 v[194:195], off
	s_add_i32 m0, s33, 0x2000
	s_add_u32 s88, s70, 0x40000
	v_lshl_add_u64 v[230:231], s[70:71], 0, v[166:167]
	s_addc_u32 s89, s71, 0
	s_add_i32 s33, s91, s76
	global_load_lds_dwordx4 v[230:231], off
	v_lshl_add_u64 v[232:233], s[88:89], 0, v[162:163]
	s_mov_b32 m0, s33
	v_lshl_add_u64 v[234:235], s[72:73], 0, v[164:165]
	global_load_lds_dwordx4 v[232:233], off
	v_lshl_add_u64 v[232:233], s[88:89], 0, v[166:167]
	s_add_i32 m0, s33, 0x2000
	s_nop 0
	global_load_lds_dwordx4 v[232:233], off
	v_lshl_add_u64 v[232:233], s[72:73], 0, v[160:161]
	s_mov_b32 m0, s77
	s_nop 0
	global_load_lds_dwordx4 v[232:233], off
	s_mov_b32 m0, s78
	s_nop 0
	global_load_lds_dwordx4 v[234:235], off
	s_waitcnt vmcnt(8)
	s_waitcnt lgkmcnt(0)
	s_barrier
	s_setprio 1
	s_waitcnt lgkmcnt(0)
	v_mfma_f32_16x16x32_bf16 v[76:79], v[32:35], v[182:185], v[76:79]
	v_mfma_f32_16x16x32_bf16 v[72:75], v[40:43], v[182:185], v[72:75]
	v_mfma_f32_16x16x32_bf16 v[60:63], v[32:35], v[190:193], v[60:63]
	v_mfma_f32_16x16x32_bf16 v[56:59], v[40:43], v[190:193], v[56:59]
	v_mfma_f32_16x16x32_bf16 v[28:31], v[32:35], v[214:217], v[28:31]
	v_mfma_f32_16x16x32_bf16 v[24:27], v[40:43], v[214:217], v[24:27]
	v_mfma_f32_16x16x32_bf16 v[12:15], v[32:35], v[222:225], v[12:15]
	v_mfma_f32_16x16x32_bf16 v[8:11], v[40:43], v[222:225], v[8:11]
	v_mfma_f32_16x16x32_bf16 v[76:79], v[36:39], v[186:189], v[76:79]
	v_mfma_f32_16x16x32_bf16 v[72:75], v[44:47], v[186:189], v[72:75]
	v_mfma_f32_16x16x32_bf16 v[60:63], v[36:39], v[198:201], v[60:63]
	v_mfma_f32_16x16x32_bf16 v[56:59], v[44:47], v[198:201], v[56:59]
	v_mfma_f32_16x16x32_bf16 v[28:31], v[36:39], v[218:221], v[28:31]
	v_mfma_f32_16x16x32_bf16 v[24:27], v[44:47], v[218:221], v[24:27]
	v_mfma_f32_16x16x32_bf16 v[12:15], v[36:39], v[226:229], v[12:15]
	v_mfma_f32_16x16x32_bf16 v[8:11], v[44:47], v[226:229], v[8:11]
	s_setprio 0
	s_setprio 1
	v_mfma_f32_16x16x32_bf16 v[20:23], v[144:147], v[214:217], v[20:23]
	v_mfma_f32_16x16x32_bf16 v[16:19], v[152:155], v[214:217], v[16:19]
	v_mfma_f32_16x16x32_bf16 v[4:7], v[144:147], v[222:225], v[4:7]
	v_mfma_f32_16x16x32_bf16 v[0:3], v[152:155], v[222:225], v[0:3]
	v_mfma_f32_16x16x32_bf16 v[32:35], v[144:147], v[182:185], v[68:71]
	v_mfma_f32_16x16x32_bf16 v[36:39], v[152:155], v[182:185], v[64:67]
	v_mfma_f32_16x16x32_bf16 v[40:43], v[144:147], v[190:193], v[52:55]
	v_mfma_f32_16x16x32_bf16 v[44:47], v[152:155], v[190:193], v[48:51]
	v_mfma_f32_16x16x32_bf16 v[20:23], v[148:151], v[218:221], v[20:23]
	v_mfma_f32_16x16x32_bf16 v[16:19], v[156:159], v[218:221], v[16:19]
	v_mfma_f32_16x16x32_bf16 v[4:7], v[148:151], v[226:229], v[4:7]
	v_mfma_f32_16x16x32_bf16 v[0:3], v[156:159], v[226:229], v[0:3]
	v_mfma_f32_16x16x32_bf16 v[32:35], v[148:151], v[186:189], v[32:35]
	v_mfma_f32_16x16x32_bf16 v[36:39], v[156:159], v[186:189], v[36:39]
	v_mfma_f32_16x16x32_bf16 v[40:43], v[148:151], v[198:201], v[40:43]
	v_mfma_f32_16x16x32_bf16 v[44:47], v[156:159], v[198:201], v[44:47]
	s_setprio 0
	s_barrier
	s_add_i32 s33, 0, 0x18000
	s_add_i32 s57, 0, 0x1c000
	v_add_u32_e32 v68, s33, v207
	v_add_u32_e32 v156, s57, v207
	ds_read_b128 v[48:51], v68
	ds_read_b128 v[52:55], v68 offset:1024
	ds_read_b128 v[64:67], v68 offset:2048
	ds_read_b128 v[68:71], v68 offset:3072
	ds_read_b128 v[144:147], v156
	ds_read_b128 v[148:151], v156 offset:1024
	ds_read_b128 v[152:155], v156 offset:2048
	ds_read_b128 v[156:159], v156 offset:3072
	s_add_u32 s72, s72, 0x40000
	s_addc_u32 s73, s73, 0
	s_mov_b32 m0, s79
	v_lshl_add_u64 v[236:237], s[72:73], 0, v[160:161]
	ds_read_b128 v[182:185], v210 offset:32768
	ds_read_b128 v[186:189], v210 offset:33792
	ds_read_b128 v[190:193], v210 offset:34816
	ds_read_b128 v[198:201], v210 offset:35840
	ds_read_b128 v[214:217], v210 offset:36864
	ds_read_b128 v[218:221], v210 offset:37888
	ds_read_b128 v[222:225], v210 offset:38912
	ds_read_b128 v[226:229], v210 offset:39936
	global_load_lds_dwordx4 v[236:237], off
	v_lshl_add_u64 v[236:237], s[72:73], 0, v[164:165]
	s_mov_b32 m0, s82
	s_nop 0
	global_load_lds_dwordx4 v[236:237], off
	s_waitcnt vmcnt(8)
	s_waitcnt lgkmcnt(0)
	s_barrier
	s_setprio 1
	s_waitcnt lgkmcnt(0)
	v_mfma_f32_16x16x32_bf16 v[140:143], v[48:51], v[182:185], v[140:143]
	v_mfma_f32_16x16x32_bf16 v[136:139], v[64:67], v[182:185], v[136:139]
	v_mfma_f32_16x16x32_bf16 v[124:127], v[48:51], v[190:193], v[124:127]
	v_mfma_f32_16x16x32_bf16 v[120:123], v[64:67], v[190:193], v[120:123]
	v_mfma_f32_16x16x32_bf16 v[108:111], v[48:51], v[214:217], v[108:111]
	v_mfma_f32_16x16x32_bf16 v[104:107], v[64:67], v[214:217], v[104:107]
	v_mfma_f32_16x16x32_bf16 v[92:95], v[48:51], v[222:225], v[92:95]
	v_mfma_f32_16x16x32_bf16 v[88:91], v[64:67], v[222:225], v[88:91]
	v_mfma_f32_16x16x32_bf16 v[140:143], v[52:55], v[186:189], v[140:143]
	v_mfma_f32_16x16x32_bf16 v[136:139], v[68:71], v[186:189], v[136:139]
	v_mfma_f32_16x16x32_bf16 v[124:127], v[52:55], v[198:201], v[124:127]
	v_mfma_f32_16x16x32_bf16 v[120:123], v[68:71], v[198:201], v[120:123]
	v_mfma_f32_16x16x32_bf16 v[108:111], v[52:55], v[218:221], v[108:111]
	v_mfma_f32_16x16x32_bf16 v[104:107], v[68:71], v[218:221], v[104:107]
	v_mfma_f32_16x16x32_bf16 v[92:95], v[52:55], v[226:229], v[92:95]
	v_mfma_f32_16x16x32_bf16 v[88:91], v[68:71], v[226:229], v[88:91]
	s_setprio 0
	s_setprio 1
	v_mfma_f32_16x16x32_bf16 v[132:135], v[144:147], v[182:185], v[132:135]
	v_mfma_f32_16x16x32_bf16 v[128:131], v[152:155], v[182:185], v[128:131]
	v_mfma_f32_16x16x32_bf16 v[116:119], v[144:147], v[190:193], v[116:119]
	v_mfma_f32_16x16x32_bf16 v[112:115], v[152:155], v[190:193], v[112:115]
	v_mfma_f32_16x16x32_bf16 v[100:103], v[144:147], v[214:217], v[100:103]
	v_mfma_f32_16x16x32_bf16 v[96:99], v[152:155], v[214:217], v[96:99]
	v_mfma_f32_16x16x32_bf16 v[84:87], v[144:147], v[222:225], v[84:87]
	v_mfma_f32_16x16x32_bf16 v[80:83], v[152:155], v[222:225], v[80:83]
	v_mfma_f32_16x16x32_bf16 v[132:135], v[148:151], v[186:189], v[132:135]
	v_mfma_f32_16x16x32_bf16 v[128:131], v[156:159], v[186:189], v[128:131]
	v_mfma_f32_16x16x32_bf16 v[116:119], v[148:151], v[198:201], v[116:119]
	v_mfma_f32_16x16x32_bf16 v[112:115], v[156:159], v[198:201], v[112:115]
	v_mfma_f32_16x16x32_bf16 v[100:103], v[148:151], v[218:221], v[100:103]
	v_mfma_f32_16x16x32_bf16 v[96:99], v[156:159], v[218:221], v[96:99]
	v_mfma_f32_16x16x32_bf16 v[84:87], v[148:151], v[226:229], v[84:87]
	v_mfma_f32_16x16x32_bf16 v[80:83], v[156:159], v[226:229], v[80:83]
	s_setprio 0
	s_barrier
	s_add_i32 s33, s33, s76
	v_lshl_add_u64 v[194:195], v[194:195], 0, s[16:17]
	s_mov_b32 m0, s33
	ds_read_b128 v[182:185], v210 offset:49152
	ds_read_b128 v[186:189], v210 offset:50176
	ds_read_b128 v[190:193], v210 offset:51200
	ds_read_b128 v[198:201], v210 offset:52224
	ds_read_b128 v[214:217], v210 offset:53248
	ds_read_b128 v[218:221], v210 offset:54272
	ds_read_b128 v[222:225], v210 offset:55296
	ds_read_b128 v[226:229], v210 offset:56320
	global_load_lds_dwordx4 v[194:195], off
	s_add_i32 m0, s33, 0x2000
	s_add_u32 s70, s70, 0x40080
	v_lshl_add_u64 v[194:195], v[230:231], 0, s[16:17]
	s_addc_u32 s71, s71, 0
	s_add_i32 s33, s57, s76
	global_load_lds_dwordx4 v[194:195], off
	v_lshl_add_u64 v[194:195], s[70:71], 0, v[162:163]
	s_mov_b32 m0, s33
	s_nop 0
	global_load_lds_dwordx4 v[194:195], off
	v_lshl_add_u64 v[194:195], s[70:71], 0, v[166:167]
	s_add_i32 m0, s33, 0x2000
	s_nop 0
	global_load_lds_dwordx4 v[194:195], off
	v_lshl_add_u64 v[194:195], v[232:233], 0, s[16:17]
	s_mov_b32 m0, s85
	s_nop 0
	global_load_lds_dwordx4 v[194:195], off
	v_lshl_add_u64 v[194:195], v[234:235], 0, s[16:17]
	s_mov_b32 m0, s86
	s_nop 0
	global_load_lds_dwordx4 v[194:195], off
	s_waitcnt vmcnt(8)
	s_waitcnt lgkmcnt(0)
	s_barrier
	s_setprio 1
	s_waitcnt lgkmcnt(0)
	v_mfma_f32_16x16x32_bf16 v[76:79], v[48:51], v[182:185], v[76:79]
	v_mfma_f32_16x16x32_bf16 v[72:75], v[64:67], v[182:185], v[72:75]
	v_mfma_f32_16x16x32_bf16 v[60:63], v[48:51], v[190:193], v[60:63]
	v_mfma_f32_16x16x32_bf16 v[56:59], v[64:67], v[190:193], v[56:59]
	v_mfma_f32_16x16x32_bf16 v[28:31], v[48:51], v[214:217], v[28:31]
	v_mfma_f32_16x16x32_bf16 v[24:27], v[64:67], v[214:217], v[24:27]
	v_mfma_f32_16x16x32_bf16 v[12:15], v[48:51], v[222:225], v[12:15]
	v_mfma_f32_16x16x32_bf16 v[8:11], v[64:67], v[222:225], v[8:11]
	v_mfma_f32_16x16x32_bf16 v[76:79], v[52:55], v[186:189], v[76:79]
	v_mfma_f32_16x16x32_bf16 v[72:75], v[68:71], v[186:189], v[72:75]
	v_mfma_f32_16x16x32_bf16 v[60:63], v[52:55], v[198:201], v[60:63]
	v_mfma_f32_16x16x32_bf16 v[56:59], v[68:71], v[198:201], v[56:59]
	v_mfma_f32_16x16x32_bf16 v[28:31], v[52:55], v[218:221], v[28:31]
	v_mfma_f32_16x16x32_bf16 v[24:27], v[68:71], v[218:221], v[24:27]
	v_mfma_f32_16x16x32_bf16 v[12:15], v[52:55], v[226:229], v[12:15]
	v_mfma_f32_16x16x32_bf16 v[8:11], v[68:71], v[226:229], v[8:11]
	s_setprio 0
	s_setprio 1
	v_mfma_f32_16x16x32_bf16 v[32:35], v[144:147], v[182:185], v[32:35]
	v_mfma_f32_16x16x32_bf16 v[68:71], v[148:151], v[186:189], v[32:35]
	v_mfma_f32_16x16x32_bf16 v[32:35], v[152:155], v[182:185], v[36:39]
	v_mfma_f32_16x16x32_bf16 v[64:67], v[156:159], v[186:189], v[32:35]
	v_mfma_f32_16x16x32_bf16 v[32:35], v[144:147], v[190:193], v[40:43]
	v_mfma_f32_16x16x32_bf16 v[52:55], v[148:151], v[198:201], v[32:35]
	v_mfma_f32_16x16x32_bf16 v[32:35], v[152:155], v[190:193], v[44:47]
	v_mfma_f32_16x16x32_bf16 v[20:23], v[144:147], v[214:217], v[20:23]
	v_mfma_f32_16x16x32_bf16 v[16:19], v[152:155], v[214:217], v[16:19]
	v_mfma_f32_16x16x32_bf16 v[4:7], v[144:147], v[222:225], v[4:7]
	v_mfma_f32_16x16x32_bf16 v[0:3], v[152:155], v[222:225], v[0:3]
	v_mfma_f32_16x16x32_bf16 v[48:51], v[156:159], v[198:201], v[32:35]
	v_mfma_f32_16x16x32_bf16 v[20:23], v[148:151], v[218:221], v[20:23]
	v_mfma_f32_16x16x32_bf16 v[16:19], v[156:159], v[218:221], v[16:19]
	v_mfma_f32_16x16x32_bf16 v[4:7], v[148:151], v[226:229], v[4:7]
	v_mfma_f32_16x16x32_bf16 v[0:3], v[156:159], v[226:229], v[0:3]
	s_setprio 0
	s_add_i32 s56, s56, 2
	s_add_u32 s68, s68, 0x100
	s_addc_u32 s69, s69, 0
	s_add_u32 s14, s14, 0x100
	s_addc_u32 s15, s15, 0
	s_cmp_gt_u32 s56, 13
	s_barrier
	s_cbranch_scc0 .LBB0_374
	s_and_b64 vcc, exec, s[18:19]
	s_cbranch_vccz .LBB0_377
	s_barrier

.LBB0_758:
	ds_read_b128 v[144:147], v153
	ds_read_b128 v[156:159], v153 offset:1024
	ds_read_b128 v[160:163], v153 offset:2048
	ds_read_b128 v[164:167], v153 offset:3072
	ds_read_b128 v[168:171], v154
	ds_read_b128 v[172:175], v154 offset:1024
	ds_read_b128 v[176:179], v154 offset:2048
	ds_read_b128 v[180:183], v154 offset:3072
	s_add_u32 s40, s38, 0xfffc0080
	s_addc_u32 s41, s39, -1
	s_cmp_eq_u32 s57, 12
	s_cselect_b32 s43, s21, s41
	s_cselect_b32 s42, s53, s40
	s_cselect_b32 s41, s19, s56
	s_cselect_b32 s40, s54, s55
	v_lshl_add_u64 v[148:149], s[38:39], 0, v[136:137]
	s_add_i32 m0, s27, 0xc000
	ds_read_b128 v[184:187], v155
	ds_read_b128 v[188:191], v155 offset:1024
	ds_read_b128 v[192:195], v155 offset:2048
	ds_read_b128 v[196:199], v155 offset:3072
	ds_read_b128 v[200:203], v155 offset:4096
	ds_read_b128 v[204:207], v155 offset:5120
	ds_read_b128 v[208:211], v155 offset:6144
	ds_read_b128 v[212:215], v155 offset:7168
	global_load_lds_dwordx4 v[148:149], off
	v_lshl_add_u64 v[148:149], s[38:39], 0, v[138:139]
	s_add_i32 m0, s27, 0xe000
	s_nop 0
	global_load_lds_dwordx4 v[148:149], off
	s_waitcnt vmcnt(8)
	s_waitcnt lgkmcnt(0)
	s_barrier
	s_setprio 1
	s_waitcnt lgkmcnt(0)
	v_mfma_f32_16x16x32_bf16 v[124:127], v[144:147], v[184:187], v[124:127]
	v_mfma_f32_16x16x32_bf16 v[120:123], v[160:163], v[184:187], v[120:123]
	v_mfma_f32_16x16x32_bf16 v[108:111], v[144:147], v[192:195], v[108:111]
	v_mfma_f32_16x16x32_bf16 v[104:107], v[160:163], v[192:195], v[104:107]
	v_mfma_f32_16x16x32_bf16 v[92:95], v[144:147], v[200:203], v[92:95]
	v_mfma_f32_16x16x32_bf16 v[88:91], v[160:163], v[200:203], v[88:91]
	v_mfma_f32_16x16x32_bf16 v[76:79], v[144:147], v[208:211], v[76:79]
	v_mfma_f32_16x16x32_bf16 v[72:75], v[160:163], v[208:211], v[72:75]
	v_mfma_f32_16x16x32_bf16 v[124:127], v[156:159], v[188:191], v[124:127]
	v_mfma_f32_16x16x32_bf16 v[120:123], v[164:167], v[188:191], v[120:123]
	v_mfma_f32_16x16x32_bf16 v[108:111], v[156:159], v[196:199], v[108:111]
	v_mfma_f32_16x16x32_bf16 v[104:107], v[164:167], v[196:199], v[104:107]
	v_mfma_f32_16x16x32_bf16 v[92:95], v[156:159], v[204:207], v[92:95]
	v_mfma_f32_16x16x32_bf16 v[88:91], v[164:167], v[204:207], v[88:91]
	v_mfma_f32_16x16x32_bf16 v[76:79], v[156:159], v[212:215], v[76:79]
	v_mfma_f32_16x16x32_bf16 v[72:75], v[164:167], v[212:215], v[72:75]
	s_setprio 0
	s_setprio 1
	v_mfma_f32_16x16x32_bf16 v[116:119], v[168:171], v[184:187], v[116:119]
	v_mfma_f32_16x16x32_bf16 v[112:115], v[176:179], v[184:187], v[112:115]
	v_mfma_f32_16x16x32_bf16 v[100:103], v[168:171], v[192:195], v[100:103]
	v_mfma_f32_16x16x32_bf16 v[96:99], v[176:179], v[192:195], v[96:99]
	v_mfma_f32_16x16x32_bf16 v[84:87], v[168:171], v[200:203], v[84:87]
	v_mfma_f32_16x16x32_bf16 v[80:83], v[176:179], v[200:203], v[80:83]
	v_mfma_f32_16x16x32_bf16 v[68:71], v[168:171], v[208:211], v[68:71]
	v_mfma_f32_16x16x32_bf16 v[64:67], v[176:179], v[208:211], v[64:67]
	v_mfma_f32_16x16x32_bf16 v[116:119], v[172:175], v[188:191], v[116:119]
	v_mfma_f32_16x16x32_bf16 v[112:115], v[180:183], v[188:191], v[112:115]
	v_mfma_f32_16x16x32_bf16 v[100:103], v[172:175], v[196:199], v[100:103]
	v_mfma_f32_16x16x32_bf16 v[96:99], v[180:183], v[196:199], v[96:99]
	v_mfma_f32_16x16x32_bf16 v[84:87], v[172:175], v[204:207], v[84:87]
	v_mfma_f32_16x16x32_bf16 v[80:83], v[180:183], v[204:207], v[80:83]
	v_mfma_f32_16x16x32_bf16 v[68:71], v[172:175], v[212:215], v[68:71]
	v_mfma_f32_16x16x32_bf16 v[64:67], v[180:183], v[212:215], v[64:67]
	s_setprio 0
	s_barrier
	s_add_i32 s58, s50, s33
	v_lshl_add_u64 v[148:149], s[40:41], 0, v[130:131]
	s_mov_b32 m0, s58
	ds_read_b128 v[184:187], v155 offset:16384
	ds_read_b128 v[188:191], v155 offset:17408
	ds_read_b128 v[192:195], v155 offset:18432
	ds_read_b128 v[196:199], v155 offset:19456
	ds_read_b128 v[200:203], v155 offset:20480
	ds_read_b128 v[204:207], v155 offset:21504
	ds_read_b128 v[208:211], v155 offset:22528
	ds_read_b128 v[212:215], v155 offset:23552
	global_load_lds_dwordx4 v[148:149], off
	s_add_i32 m0, s58, 0x2000
	s_add_u32 s58, s40, 0x40000
	v_lshl_add_u64 v[216:217], s[40:41], 0, v[134:135]
	s_addc_u32 s59, s41, 0
	s_add_i32 s60, s51, s33
	global_load_lds_dwordx4 v[216:217], off
	v_lshl_add_u64 v[218:219], s[58:59], 0, v[130:131]
	s_mov_b32 m0, s60
	v_lshl_add_u64 v[220:221], s[42:43], 0, v[132:133]
	global_load_lds_dwordx4 v[218:219], off
	v_lshl_add_u64 v[218:219], s[58:59], 0, v[134:135]
	s_add_i32 m0, s60, 0x2000
	s_nop 0
	global_load_lds_dwordx4 v[218:219], off
	v_lshl_add_u64 v[218:219], s[42:43], 0, v[128:129]
	s_mov_b32 m0, s27
	s_nop 0
	global_load_lds_dwordx4 v[218:219], off
	s_mov_b32 m0, s44
	s_nop 0
	global_load_lds_dwordx4 v[220:221], off
	s_waitcnt vmcnt(8)
	s_waitcnt lgkmcnt(0)
	s_barrier
	s_setprio 1
	s_waitcnt lgkmcnt(0)
	v_mfma_f32_16x16x32_bf16 v[60:63], v[144:147], v[184:187], v[60:63]
	v_mfma_f32_16x16x32_bf16 v[56:59], v[160:163], v[184:187], v[56:59]
	v_mfma_f32_16x16x32_bf16 v[44:47], v[144:147], v[192:195], v[44:47]
	v_mfma_f32_16x16x32_bf16 v[40:43], v[160:163], v[192:195], v[40:43]
	v_mfma_f32_16x16x32_bf16 v[28:31], v[144:147], v[200:203], v[28:31]
	v_mfma_f32_16x16x32_bf16 v[24:27], v[160:163], v[200:203], v[24:27]
	v_mfma_f32_16x16x32_bf16 v[12:15], v[144:147], v[208:211], v[12:15]
	v_mfma_f32_16x16x32_bf16 v[8:11], v[160:163], v[208:211], v[8:11]
	v_mfma_f32_16x16x32_bf16 v[60:63], v[156:159], v[188:191], v[60:63]
	v_mfma_f32_16x16x32_bf16 v[56:59], v[164:167], v[188:191], v[56:59]
	v_mfma_f32_16x16x32_bf16 v[44:47], v[156:159], v[196:199], v[44:47]
	v_mfma_f32_16x16x32_bf16 v[40:43], v[164:167], v[196:199], v[40:43]
	v_mfma_f32_16x16x32_bf16 v[28:31], v[156:159], v[204:207], v[28:31]
	v_mfma_f32_16x16x32_bf16 v[24:27], v[164:167], v[204:207], v[24:27]
	v_mfma_f32_16x16x32_bf16 v[12:15], v[156:159], v[212:215], v[12:15]
	v_mfma_f32_16x16x32_bf16 v[8:11], v[164:167], v[212:215], v[8:11]
	s_setprio 0
	s_setprio 1
	v_mfma_f32_16x16x32_bf16 v[52:55], v[168:171], v[184:187], v[52:55]
	v_mfma_f32_16x16x32_bf16 v[48:51], v[176:179], v[184:187], v[48:51]
	v_mfma_f32_16x16x32_bf16 v[36:39], v[168:171], v[192:195], v[36:39]
	v_mfma_f32_16x16x32_bf16 v[32:35], v[176:179], v[192:195], v[32:35]
	v_mfma_f32_16x16x32_bf16 v[20:23], v[168:171], v[200:203], v[20:23]
	v_mfma_f32_16x16x32_bf16 v[16:19], v[176:179], v[200:203], v[16:19]
	v_mfma_f32_16x16x32_bf16 v[4:7], v[168:171], v[208:211], v[4:7]
	v_mfma_f32_16x16x32_bf16 v[0:3], v[176:179], v[208:211], v[0:3]
	v_mfma_f32_16x16x32_bf16 v[52:55], v[172:175], v[188:191], v[52:55]
	v_mfma_f32_16x16x32_bf16 v[48:51], v[180:183], v[188:191], v[48:51]
	v_mfma_f32_16x16x32_bf16 v[36:39], v[172:175], v[196:199], v[36:39]
	v_mfma_f32_16x16x32_bf16 v[32:35], v[180:183], v[196:199], v[32:35]
	v_mfma_f32_16x16x32_bf16 v[20:23], v[172:175], v[204:207], v[20:23]
	v_mfma_f32_16x16x32_bf16 v[16:19], v[180:183], v[204:207], v[16:19]
	v_mfma_f32_16x16x32_bf16 v[4:7], v[172:175], v[212:215], v[4:7]
	v_mfma_f32_16x16x32_bf16 v[0:3], v[180:183], v[212:215], v[0:3]
	s_setprio 0
	s_barrier
	s_add_i32 s58, 0, 0x18000
	s_add_i32 s59, 0, 0x1c000
	v_add_u32_e32 v164, s58, v151
	v_add_u32_e32 v180, s59, v151
	ds_read_b128 v[144:147], v164
	ds_read_b128 v[156:159], v164 offset:1024
	ds_read_b128 v[160:163], v164 offset:2048
	ds_read_b128 v[164:167], v164 offset:3072
	ds_read_b128 v[168:171], v180
	ds_read_b128 v[172:175], v180 offset:1024
	ds_read_b128 v[176:179], v180 offset:2048
	ds_read_b128 v[180:183], v180 offset:3072
	s_add_u32 s42, s42, 0x40000
	s_addc_u32 s43, s43, 0
	s_mov_b32 m0, s45
	v_lshl_add_u64 v[222:223], s[42:43], 0, v[128:129]
	ds_read_b128 v[184:187], v155 offset:32768
	ds_read_b128 v[188:191], v155 offset:33792
	ds_read_b128 v[192:195], v155 offset:34816
	ds_read_b128 v[196:199], v155 offset:35840
	ds_read_b128 v[200:203], v155 offset:36864
	ds_read_b128 v[204:207], v155 offset:37888
	ds_read_b128 v[208:211], v155 offset:38912
	ds_read_b128 v[212:215], v155 offset:39936
	global_load_lds_dwordx4 v[222:223], off
	v_lshl_add_u64 v[222:223], s[42:43], 0, v[132:133]
	s_mov_b32 m0, s46
	s_nop 0
	global_load_lds_dwordx4 v[222:223], off
	s_waitcnt vmcnt(8)
	s_waitcnt lgkmcnt(0)
	s_barrier
	s_setprio 1
	s_waitcnt lgkmcnt(0)
	v_mfma_f32_16x16x32_bf16 v[124:127], v[144:147], v[184:187], v[124:127]
	v_mfma_f32_16x16x32_bf16 v[120:123], v[160:163], v[184:187], v[120:123]
	v_mfma_f32_16x16x32_bf16 v[108:111], v[144:147], v[192:195], v[108:111]
	v_mfma_f32_16x16x32_bf16 v[104:107], v[160:163], v[192:195], v[104:107]
	v_mfma_f32_16x16x32_bf16 v[92:95], v[144:147], v[200:203], v[92:95]
	v_mfma_f32_16x16x32_bf16 v[88:91], v[160:163], v[200:203], v[88:91]
	v_mfma_f32_16x16x32_bf16 v[76:79], v[144:147], v[208:211], v[76:79]
	v_mfma_f32_16x16x32_bf16 v[72:75], v[160:163], v[208:211], v[72:75]
	v_mfma_f32_16x16x32_bf16 v[124:127], v[156:159], v[188:191], v[124:127]
	v_mfma_f32_16x16x32_bf16 v[120:123], v[164:167], v[188:191], v[120:123]
	v_mfma_f32_16x16x32_bf16 v[108:111], v[156:159], v[196:199], v[108:111]
	v_mfma_f32_16x16x32_bf16 v[104:107], v[164:167], v[196:199], v[104:107]
	v_mfma_f32_16x16x32_bf16 v[92:95], v[156:159], v[204:207], v[92:95]
	v_mfma_f32_16x16x32_bf16 v[88:91], v[164:167], v[204:207], v[88:91]
	v_mfma_f32_16x16x32_bf16 v[76:79], v[156:159], v[212:215], v[76:79]
	v_mfma_f32_16x16x32_bf16 v[72:75], v[164:167], v[212:215], v[72:75]
	s_setprio 0
	s_setprio 1
	v_mfma_f32_16x16x32_bf16 v[116:119], v[168:171], v[184:187], v[116:119]
	v_mfma_f32_16x16x32_bf16 v[112:115], v[176:179], v[184:187], v[112:115]
	v_mfma_f32_16x16x32_bf16 v[100:103], v[168:171], v[192:195], v[100:103]
	v_mfma_f32_16x16x32_bf16 v[96:99], v[176:179], v[192:195], v[96:99]
	v_mfma_f32_16x16x32_bf16 v[84:87], v[168:171], v[200:203], v[84:87]
	v_mfma_f32_16x16x32_bf16 v[80:83], v[176:179], v[200:203], v[80:83]
	v_mfma_f32_16x16x32_bf16 v[68:71], v[168:171], v[208:211], v[68:71]
	v_mfma_f32_16x16x32_bf16 v[64:67], v[176:179], v[208:211], v[64:67]
	v_mfma_f32_16x16x32_bf16 v[116:119], v[172:175], v[188:191], v[116:119]
	v_mfma_f32_16x16x32_bf16 v[112:115], v[180:183], v[188:191], v[112:115]
	v_mfma_f32_16x16x32_bf16 v[100:103], v[172:175], v[196:199], v[100:103]
	v_mfma_f32_16x16x32_bf16 v[96:99], v[180:183], v[196:199], v[96:99]
	v_mfma_f32_16x16x32_bf16 v[84:87], v[172:175], v[204:207], v[84:87]
	v_mfma_f32_16x16x32_bf16 v[80:83], v[180:183], v[204:207], v[80:83]
	v_mfma_f32_16x16x32_bf16 v[68:71], v[172:175], v[212:215], v[68:71]
	v_mfma_f32_16x16x32_bf16 v[64:67], v[180:183], v[212:215], v[64:67]
	s_setprio 0
	s_barrier
	s_add_i32 s42, s58, s33
	v_lshl_add_u64 v[148:149], v[148:149], 0, s[6:7]
	s_mov_b32 m0, s42
	ds_read_b128 v[184:187], v155 offset:49152
	ds_read_b128 v[188:191], v155 offset:50176
	ds_read_b128 v[192:195], v155 offset:51200
	ds_read_b128 v[196:199], v155 offset:52224
	ds_read_b128 v[200:203], v155 offset:53248
	ds_read_b128 v[204:207], v155 offset:54272
	ds_read_b128 v[208:211], v155 offset:55296
	ds_read_b128 v[212:215], v155 offset:56320
	global_load_lds_dwordx4 v[148:149], off
	s_add_i32 m0, s42, 0x2000
	s_add_u32 s40, s40, 0x40080
	v_lshl_add_u64 v[148:149], v[216:217], 0, s[6:7]
	s_addc_u32 s41, s41, 0
	s_add_i32 s42, s59, s33
	global_load_lds_dwordx4 v[148:149], off
	v_lshl_add_u64 v[148:149], s[40:41], 0, v[130:131]
	s_mov_b32 m0, s42
	s_nop 0
	global_load_lds_dwordx4 v[148:149], off
	v_lshl_add_u64 v[148:149], s[40:41], 0, v[134:135]
	s_add_i32 m0, s42, 0x2000
	s_nop 0
	global_load_lds_dwordx4 v[148:149], off
	v_lshl_add_u64 v[148:149], v[218:219], 0, s[6:7]
	s_mov_b32 m0, s48
	s_nop 0
	global_load_lds_dwordx4 v[148:149], off
	v_lshl_add_u64 v[148:149], v[220:221], 0, s[6:7]
	s_mov_b32 m0, s49
	s_nop 0
	global_load_lds_dwordx4 v[148:149], off
	s_waitcnt vmcnt(8)
	s_waitcnt lgkmcnt(0)
	s_barrier
	s_setprio 1
	s_waitcnt lgkmcnt(0)
	v_mfma_f32_16x16x32_bf16 v[60:63], v[144:147], v[184:187], v[60:63]
	v_mfma_f32_16x16x32_bf16 v[56:59], v[160:163], v[184:187], v[56:59]
	v_mfma_f32_16x16x32_bf16 v[44:47], v[144:147], v[192:195], v[44:47]
	v_mfma_f32_16x16x32_bf16 v[40:43], v[160:163], v[192:195], v[40:43]
	v_mfma_f32_16x16x32_bf16 v[28:31], v[144:147], v[200:203], v[28:31]
	v_mfma_f32_16x16x32_bf16 v[24:27], v[160:163], v[200:203], v[24:27]
	v_mfma_f32_16x16x32_bf16 v[12:15], v[144:147], v[208:211], v[12:15]
	v_mfma_f32_16x16x32_bf16 v[8:11], v[160:163], v[208:211], v[8:11]
	v_mfma_f32_16x16x32_bf16 v[60:63], v[156:159], v[188:191], v[60:63]
	v_mfma_f32_16x16x32_bf16 v[56:59], v[164:167], v[188:191], v[56:59]
	v_mfma_f32_16x16x32_bf16 v[44:47], v[156:159], v[196:199], v[44:47]
	v_mfma_f32_16x16x32_bf16 v[40:43], v[164:167], v[196:199], v[40:43]
	v_mfma_f32_16x16x32_bf16 v[28:31], v[156:159], v[204:207], v[28:31]
	v_mfma_f32_16x16x32_bf16 v[24:27], v[164:167], v[204:207], v[24:27]
	v_mfma_f32_16x16x32_bf16 v[12:15], v[156:159], v[212:215], v[12:15]
	v_mfma_f32_16x16x32_bf16 v[8:11], v[164:167], v[212:215], v[8:11]
	s_setprio 0
	s_setprio 1
	v_mfma_f32_16x16x32_bf16 v[52:55], v[168:171], v[184:187], v[52:55]
	v_mfma_f32_16x16x32_bf16 v[48:51], v[176:179], v[184:187], v[48:51]
	v_mfma_f32_16x16x32_bf16 v[36:39], v[168:171], v[192:195], v[36:39]
	v_mfma_f32_16x16x32_bf16 v[32:35], v[176:179], v[192:195], v[32:35]
	v_mfma_f32_16x16x32_bf16 v[20:23], v[168:171], v[200:203], v[20:23]
	v_mfma_f32_16x16x32_bf16 v[16:19], v[176:179], v[200:203], v[16:19]
	v_mfma_f32_16x16x32_bf16 v[4:7], v[168:171], v[208:211], v[4:7]
	v_mfma_f32_16x16x32_bf16 v[0:3], v[176:179], v[208:211], v[0:3]
	v_mfma_f32_16x16x32_bf16 v[52:55], v[172:175], v[188:191], v[52:55]
	v_mfma_f32_16x16x32_bf16 v[48:51], v[180:183], v[188:191], v[48:51]
	v_mfma_f32_16x16x32_bf16 v[36:39], v[172:175], v[196:199], v[36:39]
	v_mfma_f32_16x16x32_bf16 v[32:35], v[180:183], v[196:199], v[32:35]
	v_mfma_f32_16x16x32_bf16 v[20:23], v[172:175], v[204:207], v[20:23]
	v_mfma_f32_16x16x32_bf16 v[16:19], v[180:183], v[204:207], v[16:19]
	v_mfma_f32_16x16x32_bf16 v[4:7], v[172:175], v[212:215], v[4:7]
	v_mfma_f32_16x16x32_bf16 v[0:3], v[180:183], v[212:215], v[0:3]
	s_setprio 0
	s_add_i32 s57, s57, 2
	s_add_u32 s38, s38, 0x100
	s_addc_u32 s39, s39, 0
	s_add_u32 s55, s55, 0x100
	s_addc_u32 s56, s56, 0
	s_cmp_gt_u32 s57, 13
	s_barrier
	s_cbranch_scc0 .LBB0_758
	s_and_b64 vcc, exec, s[8:9]
	s_cbranch_vccz .LBB0_761
	s_barrier
